# adds: GLA scan producers stage the raw q/k chunk tiles HBM->LDS with 4 LDS-DMA loads per wave (issued one step ahead) and read their column with ds_read_u16, replacing 32 two-byte buffer loads per thr
# speedup vs baseline: 1.0055x; 1.0055x over previous
; #define LAS __attribute__((address_space(3)))
; __device__ __forceinline__ void gla_scan_phase2(LAS unsigned char* lds, const bf16_t* proj, const float* gbuf, const float* wgu  , const float* bg  ,
;                                                 bf16_t* ob0, bf16_t* ob1) {
;     ...
;         if (wave < 4) {
;             const int d = tid & 127, seg = (tid >> 7) & 1;
;             const int zd = wave;
;             bf16x8 wbh, wbl;
;             {
;                 unsigned hi_[4], lo_[4];
; #pragma unroll
;                 for (int q = 0; q < 4; ++q) {
;                     const float w0 = wgu[(size_t)(dir * 16 + 8 * hh + 2 * q) * 512 + h * 128 + 32 * zd + r], w1 = wgu[(size_t)(dir * 16 + 8 * hh + 2 * q + 1) * 512 + h * 128 + 32 * zd + r];
;                     hi_[q] = pk2(w0, w1); lo_[q] = pk2(w0 - bflo(hi_[q]), w1 - bfhi(hi_[q]));
;                 }
;                 wbh = __builtin_bit_cast(bf16x8, (u32x4){hi_[0], hi_[1], hi_[2], hi_[3]}); wbl = __builtin_bit_cast(bf16x8, (u32x4){lo_[0], lo_[1], lo_[2], lo_[3]});
;             }
;             const float zbias = bg[dir * 512 + h * 128 + 32 * zd + r];
;             const __amdgpu_buffer_rsrc_t prs = __builtin_amdgcn_make_buffer_rsrc((void*)proj, 0, (unsigned)((size_t)MTOK * GINP * 2), 0x00020000);
;             const unsigned qvoff = (unsigned)((16 * seg * GINP + h * 128 + d) * 2), vvoff = (unsigned)((16 * seg * GINP + 1024 + h * 256 + 2 * d) * 2);
;             f32x4 gna, gnb;
;             { const float* grow = gbuf + (size_t)(b * SEQ + (dir ? NCH - 1 : 0) * CH + r) * 32 + dir * 16 + 8 * hh; gna = *(const f32x4*)grow; gnb = *(const f32x4*)(grow + 4); }
;             for (int n = 0; n <= NCH; ++n) {
;                 if (n < NCH) {
;                     const int tok0 = b * SEQ + (dir ? NCH - 1 - n : n) * CH;
;                     LAS unsigned char* set = lds + (n & 1) * G2_SET;
;                     const f32x4 ga = gna, gb = gnb;
;                     const unsigned srow = (unsigned)tok0 * (unsigned)(GINP * 2);
;                     unsigned short qv[16], kv[16];
; #pragma unroll
;                     for (int ii = 0; ii < 16; ++ii) { qv[ii] = __builtin_amdgcn_raw_buffer_load_b16(prs, qvoff, srow + (unsigned)(ii * GINP * 2), 0);
;                                                        kv[ii] = __builtin_amdgcn_raw_buffer_load_b16(prs, qvoff + 1024u, srow + (unsigned)(ii * GINP * 2), 0); }
.LBB0_217:
	s_and_b64 vcc, exec, s[6:7]
	s_cbranch_vccz .LBB0_212
	s_nop 7
	v_lshl_or_b32 v0, s8, 13, v198
	s_lshl_b32 s0, s15, 7
	v_or_b32_e32 v0, s0, v0
	v_lshlrev_b32_e32 v160, 2, v0
	v_lshl_add_u64 v[0:1], s[16:17], 0, v[160:161]
	v_lshl_add_u64 v[0:1], s[22:23], 2, v[0:1]
	v_mov_b32_e32 v193, v161
	v_lshl_add_u64 v[0:1], v[0:1], 0, v[192:193]
	global_load_dword v2, v[0:1], off
	global_load_dword v3, v[0:1], off offset:2048
	s_movk_i32 s6, 0x1000
	s_lshl_b32 s9, s9, 11
	v_lshlrev_b32_e32 v160, 2, v188
	s_mov_b32 s20, 0
	v_or_b32_e32 v52, s9, v186
	s_waitcnt vmcnt(0)
	v_cvt_pk_bf16_f32 v32, v2, v3
	v_lshlrev_b32_e32 v4, 16, v32
	v_and_b32_e32 v5, 0xffff0000, v32
	v_pk_add_f32 v[2:3], v[2:3], v[4:5] neg_lo:[0,1] neg_hi:[0,1]
	s_nop 0
	v_cvt_pk_bf16_f32 v36, v2, v3
	v_add_co_u32_e32 v2, vcc, s6, v0
	s_movk_i32 s6, 0x2000
	s_nop 0
	v_addc_co_u32_e32 v3, vcc, 0, v1, vcc
	v_add_co_u32_e32 v4, vcc, s6, v0
	s_movk_i32 s6, 0x3000
	s_nop 0
	v_addc_co_u32_e32 v5, vcc, 0, v1, vcc
	global_load_dword v6, v[4:5], off offset:-4096
	global_load_dword v7, v[2:3], off offset:2048
	v_add_co_u32_e32 v0, vcc, s6, v0
	s_lshl_b32 s6, s8, 9
	s_nop 0
	v_addc_co_u32_e32 v1, vcc, 0, v1, vcc
	s_or_b32 s6, s0, s6
	s_cmp_lg_u32 s8, 0
	s_cselect_b64 s[68:69], -1, 0
	s_cmp_eq_u32 s8, 0
	s_cselect_b64 s[48:49], -1, 0
	s_waitcnt vmcnt(0)
	v_cvt_pk_bf16_f32 v33, v6, v7
	v_lshlrev_b32_e32 v2, 16, v33
	v_and_b32_e32 v3, 0xffff0000, v33
	v_pk_add_f32 v[2:3], v[6:7], v[2:3] neg_lo:[0,1] neg_hi:[0,1]
	s_nop 0
	v_cvt_pk_bf16_f32 v37, v2, v3
	global_load_dword v2, v[4:5], off
	global_load_dword v3, v[4:5], off offset:2048
	s_waitcnt vmcnt(0)
	v_cvt_pk_bf16_f32 v34, v2, v3
	v_lshlrev_b32_e32 v4, 16, v34
	v_and_b32_e32 v5, 0xffff0000, v34
	v_pk_add_f32 v[2:3], v[2:3], v[4:5] neg_lo:[0,1] neg_hi:[0,1]
	s_nop 0
	v_cvt_pk_bf16_f32 v38, v2, v3
	global_load_dword v2, v[0:1], off
	global_load_dword v3, v[0:1], off offset:2048
	s_waitcnt vmcnt(0)
	v_cvt_pk_bf16_f32 v35, v2, v3
	v_lshlrev_b32_e32 v0, 16, v35
	v_and_b32_e32 v1, 0xffff0000, v35
	v_pk_add_f32 v[0:1], v[2:3], v[0:1] neg_lo:[0,1] neg_hi:[0,1]
	s_nop 0
	v_cvt_pk_bf16_f32 v39, v0, v1
	v_add_u32_e32 v0, s6, v199
	v_ashrrev_i32_e32 v1, 31, v0
	v_lshl_add_u64 v[0:1], v[0:1], 2, s[18:19]
	global_load_dword v0, v[0:1], off
	v_or_b32_e32 v1, s0, v200
	s_and_b64 s[6:7], s[48:49], exec
	v_lshlrev_b32_e32 v50, 1, v1
	v_lshl_or_b32 v1, s15, 9, v213
	s_cselect_b32 s0, 0, 0x7e0
	v_or_b32_e32 v51, 0x800, v1
	v_or_b32_e32 v1, s0, v186
	v_or_b32_e32 v2, s9, v1
	v_ashrrev_i32_e32 v3, 31, v2
	v_readlane_b32 s6, v253, 19
	v_lshlrev_b64 v[2:3], 7, v[2:3]
	v_readlane_b32 s7, v253, 20
	s_lshl_b32 s28, s8, 6
	v_lshl_add_u64 v[48:49], v[190:191], 0, s[28:29]
	v_lshl_add_u64 v[2:3], s[6:7], 0, v[2:3]
	v_lshl_add_u64 v[2:3], v[2:3], 0, s[28:29]
	v_lshl_add_u64 v[2:3], v[2:3], 0, v[160:161]
	global_load_dwordx4 v[40:43], v[2:3], off offset:16
	global_load_dwordx4 v[44:47], v[2:3], off
	v_or_b32_e32 v53, 0x400, v50
	s_xor_b64 s[50:51], s[40:41], s[48:49]
	s_xor_b64 s[52:53], s[42:43], s[48:49]
	s_xor_b64 s[54:55], s[44:45], s[48:49]
	s_xor_b64 s[56:57], s[46:47], s[48:49]
	s_mov_b32 s8, 63
	s_waitcnt vmcnt(2)
	v_mov_b32_e32 v1, v0
	v_mov_b32_e32 v2, v0
	v_mov_b32_e32 v3, v0
	v_mov_b32_e32 v4, v0
	v_mov_b32_e32 v5, v0
	v_mov_b32_e32 v6, v0
	v_mov_b32_e32 v7, v0
	v_mov_b32_e32 v8, v0
	v_mov_b32_e32 v9, v0
	v_mov_b32_e32 v10, v0
	v_mov_b32_e32 v11, v0
	v_mov_b32_e32 v12, v0
	v_mov_b32_e32 v13, v0
	v_mov_b32_e32 v14, v0
	v_mov_b32_e32 v15, v0
	v_and_b32_e32 v172, 15, v179
	v_lshlrev_b32_e32 v172, 4, v172
	v_bfe_u32 v174, v179, 4, 2
	v_lshrrev_b32_e32 v173, 6, v179
	v_lshl_add_u32 v174, v173, 3, v174
	v_mul_u32_u24_e32 v174, 0x1a00, v174
	v_add_u32_e32 v172, v172, v174
	s_lshl_b32 s0, s15, 8
	v_add_u32_e32 v172, s0, v172
	v_lshlrev_b32_e32 v174, 11, v173
	v_add_u32_e32 v174, 0x1b600, v174
	v_and_b32_e32 v173, 0x7f, v179
	v_lshlrev_b32_e32 v173, 1, v173
	v_bfe_u32 v175, v179, 7, 1
	v_lshl_add_u32 v173, v175, 12, v173
	v_add_u32_e32 v173, 0x1b600, v173
	s_and_b64 s[6:7], s[48:49], exec
	s_cselect_b32 s0, s20, s8
	s_lshl_b32 s0, s0, 5
	s_add_i32 s0, s0, s9
	s_mulk_i32 s0, 0x1a00
	v_readfirstlane_b32 s26, v174
	s_add_u32 s78, s64, s0
	s_addc_u32 s79, s65, 0
	s_add_u32 s80, s78, 0x6800
	s_addc_u32 s81, s79, 0
	s_add_u32 s82, s78, 0x400
	s_addc_u32 s83, s79, 0
	s_add_u32 s24, s80, 0x400
	s_addc_u32 s25, s81, 0
	s_mov_b32 m0, s26
	s_nop 0
	global_load_lds_dwordx4 v172, s[78:79]
	s_add_i32 m0, s26, 0x400
	s_nop 0
	global_load_lds_dwordx4 v172, s[80:81]
	s_add_i32 m0, s26, 0x2000
	s_nop 0
	global_load_lds_dwordx4 v172, s[82:83]
	s_add_i32 m0, s26, 0x2400
	s_nop 0
	global_load_lds_dwordx4 v172, s[24:25]
	s_branch .LBB0_220
; #define LAS __attribute__((address_space(3)))
; #define MFMA16(a, b, c) __builtin_amdgcn_mfma_f32_16x16x32_bf16((a), (b), (c), 0, 0, 0)
; __device__ __forceinline__ void gla_scan_phase2(LAS unsigned char* lds, const bf16_t* proj, const float* gbuf, const float* wgu  , const float* bg  ,
;                                                 bf16_t* ob0, bf16_t* ob1) {
;     ...
;                     const f32x4 ga = gna, gb = gnb;
;                     const unsigned srow = (unsigned)tok0 * (unsigned)(GINP * 2);
;                     unsigned short qv[16], kv[16];
; #pragma unroll
;     ...
;                         unsigned c0[8], c1[8];
; #pragma unroll
;                         for (int t = 0; t < 8; ++t) { const unsigned a_ = vw[2 * t], b_ = vw[2 * t + 1]; c0[t] = (a_ & 0xffffu) | (b_ << 16); c1[t] = (a_ >> 16) | (b_ & 0xffff0000u); }
;                         *(LAS u32x4*)(set + G2_VT + (2 * d) * 80 + seg * 32) = (u32x4){c0[0], c0[1], c0[2], c0[3]};
;                         *(LAS u32x4*)(set + G2_VT + (2 * d) * 80 + seg * 32 + 16) = (u32x4){c0[4], c0[5], c0[6], c0[7]};
;                         *(LAS u32x4*)(set + G2_VT + (2 * d + 1) * 80 + seg * 32) = (u32x4){c1[0], c1[1], c1[2], c1[3]};
;                         *(LAS u32x4*)(set + G2_VT + (2 * d + 1) * 80 + seg * 32 + 16) = (u32x4){c1[4], c1[5], c1[6], c1[7]};
;                     }
;                     G2_BAR();
;                     {
;                         const int ti = wave >> 1, tj = wave & 1;
;                         f32x4 a4 = (f32x4){0.f, 0.f, 0.f, 0.f};
; #pragma unroll
;                         for (int ks = 0; ks < 4; ++ks) {
;                             const bf16x8 ka = *(const LAS bf16x8*)(lds + G2_KI + (16 * tj + fr) * 272 + ks * 64 + fq * 16);
;                             const bf16x8 qb = *(const LAS bf16x8*)(set + G2_QD + (16 * ti + fr) * 272 + ks * 64 + fq * 16);
;                             a4 = MFMA16(ka, qb, a4);
;                         }
;                         const int qi = 16 * ti + fr, kj = 16 * tj + 4 * fq;
;                         float m[4];
; #pragma unroll
;                         for (int e = 0; e < 4; ++e) { const bool keep = dir ? (kj + e > qi) : (kj + e <= qi); m[e] = keep ? a4[e] : 0.f; }
;                         u32x2 w; w.x = pk2(m[0], m[1]); w.y = pk2(m[2], m[3]);
;                         *(LAS u32x2*)(set + G2_SC + qi * 80 + kj * 2) = w;
;                     }
.LBB0_219:
	s_or_b64 exec, exec, s[6:7]
	s_waitcnt vmcnt(17)
	v_lshrrev_b32_e32 v17, 16, v68
	s_waitcnt vmcnt(15)
	v_lshrrev_b32_e32 v18, 16, v66
	s_waitcnt vmcnt(13)
	v_lshrrev_b32_e32 v19, 16, v64
	v_and_b32_e32 v16, 0xffff, v68
	v_and_or_b32 v20, v69, s77, v17
	v_and_b32_e32 v17, 0xffff, v66
	v_and_or_b32 v21, v67, s77, v18
	v_and_b32_e32 v18, 0xffff, v64
	s_waitcnt vmcnt(12)
	v_and_or_b32 v22, v65, s77, v19
	s_waitcnt vmcnt(11)
	v_and_b32_e32 v19, 0xffff, v62
	s_waitcnt vmcnt(9)
	v_lshrrev_b32_e32 v25, 16, v60
	s_waitcnt vmcnt(7)
	v_lshrrev_b32_e32 v26, 16, v58
	s_waitcnt vmcnt(5)
	v_lshrrev_b32_e32 v27, 16, v56
	v_lshl_or_b32 v16, v69, 16, v16
	v_lshl_or_b32 v17, v67, 16, v17
	v_lshl_or_b32 v18, v65, 16, v18
	v_lshl_or_b32 v19, v63, 16, v19
	v_lshrrev_b32_e32 v23, 16, v62
	v_and_b32_e32 v24, 0xffff, v60
	v_and_or_b32 v28, v61, s77, v25
	v_and_b32_e32 v25, 0xffff, v58
	v_and_or_b32 v29, v59, s77, v26
	v_and_b32_e32 v26, 0xffff, v56
	s_waitcnt vmcnt(4)
	v_and_or_b32 v30, v57, s77, v27
	s_waitcnt vmcnt(3)
	v_and_b32_e32 v27, 0xffff, v54
	v_lshrrev_b32_e32 v31, 16, v54
	v_add3_u32 v54, s15, v205, v204
	v_and_or_b32 v23, v63, s77, v23
	v_lshl_or_b32 v24, v61, 16, v24
	v_lshl_or_b32 v25, v59, 16, v25
	v_lshl_or_b32 v26, v57, 16, v26
	s_waitcnt vmcnt(2)
	v_lshl_or_b32 v27, v55, 16, v27
	v_and_or_b32 v31, v55, s77, v31
	ds_write_b128 v54, v[16:19] offset:18944
	ds_write_b128 v54, v[24:27] offset:18960
	ds_write_b128 v54, v[20:23] offset:19024
	ds_write_b128 v54, v[28:31] offset:19040
	s_waitcnt lgkmcnt(0)
	s_barrier
	s_cmp_eq_u32 s20, 63
	s_cbranch_scc1 .Lg2dma_skip
	s_and_b64 s[6:7], s[48:49], exec
	s_cselect_b32 s0, s20, s8
	s_cselect_b32 s6, 1, -1
	s_add_i32 s0, s0, s6
	s_lshl_b32 s0, s0, 5
	s_add_i32 s0, s0, s9
	s_mulk_i32 s0, 0x1a00
	v_readfirstlane_b32 s26, v174
	s_add_u32 s78, s64, s0
	s_addc_u32 s79, s65, 0
	s_add_u32 s80, s78, 0x6800
	s_addc_u32 s81, s79, 0
	s_add_u32 s82, s78, 0x400
	s_addc_u32 s83, s79, 0
	s_add_u32 s24, s80, 0x400
	s_addc_u32 s25, s81, 0
	s_mov_b32 m0, s26
	s_nop 0
	global_load_lds_dwordx4 v172, s[78:79]
	s_add_i32 m0, s26, 0x400
	s_nop 0
	global_load_lds_dwordx4 v172, s[80:81]
	s_add_i32 m0, s26, 0x2000
	s_nop 0
	global_load_lds_dwordx4 v172, s[82:83]
	s_add_i32 m0, s26, 0x2400
	s_nop 0
	global_load_lds_dwordx4 v172, s[24:25]
.Lg2dma_skip:
	v_add3_u32 v28, s15, v207, v206
	ds_read_b128 v[134:137], v233
	ds_read_b128 v[138:141], v28
	ds_read_b128 v[142:145], v233 offset:64
	ds_read_b128 v[146:149], v28 offset:64
	ds_read_b128 v[150:153], v233 offset:128
	ds_read_b128 v[154:157], v28 offset:128
	ds_read_b128 v[162:165], v233 offset:192
	ds_read_b128 v[166:169], v28 offset:192
	s_add_i32 s20, s20, 1
	s_add_i32 s8, s8, -1
	s_waitcnt lgkmcnt(6)
	v_mfma_f32_16x16x32_bf16 v[16:19], v[134:137], v[138:141], 0
	s_waitcnt lgkmcnt(4)
	v_mfma_f32_16x16x32_bf16 v[16:19], v[142:145], v[146:149], v[16:19]
	s_waitcnt lgkmcnt(2)
	v_mfma_f32_16x16x32_bf16 v[16:19], v[150:153], v[154:157], v[16:19]
	s_cmp_eq_u32 s20, 64
	s_waitcnt lgkmcnt(0)
	v_mfma_f32_16x16x32_bf16 v[16:19], v[162:165], v[166:169], v[16:19]
	s_nop 7
	v_cndmask_b32_e64 v16, 0, v16, s[50:51]
	v_cndmask_b32_e64 v17, 0, v17, s[52:53]
	v_cndmask_b32_e64 v18, 0, v18, s[54:55]
	v_cndmask_b32_e64 v19, 0, v19, s[56:57]
	v_cvt_pk_bf16_f32 v16, v16, v17
	v_cvt_pk_bf16_f32 v17, v18, v19
	v_add3_u32 v18, s15, v208, v209
	ds_write_b64 v18, v[16:17] offset:39424
	s_waitcnt lgkmcnt(0)
	s_barrier
	s_cbranch_scc1 .LBB0_211
.LBB0_220:
	s_waitcnt vmcnt(4)
	v_cvt_pk_bf16_f32 v102, v44, v45
	v_lshlrev_b32_e32 v16, 16, v102
	v_and_b32_e32 v17, 0xffff0000, v102
	v_cvt_pk_bf16_f32 v103, v46, v47
	v_cvt_pk_bf16_f32 v104, v40, v41
	v_cvt_pk_bf16_f32 v105, v42, v43
	v_pk_add_f32 v[16:17], v[44:45], v[16:17] neg_lo:[0,1] neg_hi:[0,1]
	s_and_b64 s[6:7], s[48:49], exec
	v_cvt_pk_bf16_f32 v44, v16, v17
	v_lshlrev_b32_e32 v16, 16, v103
	v_and_b32_e32 v17, 0xffff0000, v103
	v_pk_add_f32 v[16:17], v[46:47], v[16:17] neg_lo:[0,1] neg_hi:[0,1]
	s_cselect_b32 s0, s20, s8
	v_cvt_pk_bf16_f32 v45, v16, v17
	v_lshlrev_b32_e32 v16, 16, v104
	v_and_b32_e32 v17, 0xffff0000, v104
	v_pk_add_f32 v[16:17], v[40:41], v[16:17] neg_lo:[0,1] neg_hi:[0,1]
	v_lshlrev_b32_e32 v40, 16, v105
	v_cvt_pk_bf16_f32 v46, v16, v17
	v_mfma_f32_32x32x16_bf16 v[16:31], v[102:105], v[32:35], v[0:15]
	v_and_b32_e32 v41, 0xffff0000, v105
	v_add_f32_e64 v40, v42, -v40
	v_add_f32_e64 v41, v43, -v41
	s_lshl_b32 s0, s0, 5
	v_cvt_pk_bf16_f32 v47, v40, v41
	s_add_i32 s0, s0, s9
	s_mulk_i32 s0, 0x1a00
	s_or_b32 s6, s0, 0x1a00
	v_mfma_f32_32x32x16_bf16 v[16:31], v[44:47], v[32:35], v[16:31]
	s_or_b32 s7, s0, 0x3400
	s_add_i32 s15, s0, 0x4e00
	s_add_i32 s21, s0, 0x6800
	s_add_i32 s24, s0, 0x8200
	s_add_i32 s25, s0, 0x9c00
	s_add_i32 s26, s0, 0xb600
	s_add_i32 s28, s0, 0xd000
	s_add_i32 s33, s0, 0xea00
	s_add_i32 s78, s0, 0x10400
	s_add_i32 s79, s0, 0x11e00
	s_add_i32 s80, s0, 0x13800
	s_add_i32 s81, s0, 0x15200
	s_add_i32 s82, s0, 0x16c00
	s_add_i32 s83, s0, 0x18600
	s_cmp_lt_u32 s20, 63
	buffer_load_dword v68, v51, s[64:67], s0 offen
	buffer_load_dword v69, v51, s[64:67], s6 offen
	buffer_load_dword v66, v51, s[64:67], s7 offen
	buffer_load_dword v67, v51, s[64:67], s15 offen
	buffer_load_dword v64, v51, s[64:67], s21 offen
	buffer_load_dword v65, v51, s[64:67], s24 offen
	buffer_load_dword v62, v51, s[64:67], s25 offen
	buffer_load_dword v63, v51, s[64:67], s26 offen
	buffer_load_dword v60, v51, s[64:67], s28 offen
	buffer_load_dword v61, v51, s[64:67], s33 offen
	buffer_load_dword v58, v51, s[64:67], s78 offen
	buffer_load_dword v59, v51, s[64:67], s79 offen
	buffer_load_dword v56, v51, s[64:67], s80 offen
	buffer_load_dword v57, v51, s[64:67], s81 offen
	buffer_load_dword v54, v51, s[64:67], s82 offen
	buffer_load_dword v55, v51, s[64:67], s83 offen
	s_cselect_b64 s[6:7], -1, 0
	s_cmp_lg_u64 s[6:7], 0
	s_addc_u32 s0, s20, 0
	s_cmp_lg_u64 s[6:7], 0
	s_subb_u32 s6, 0, 0
	v_mfma_f32_32x32x16_bf16 v[16:31], v[102:105], v[36:39], v[16:31]
	s_add_i32 s15, s8, s6
	s_and_b64 s[6:7], s[48:49], exec
	s_cselect_b32 s0, s0, s15
	v_lshl_add_u32 v40, s0, 5, v52
	v_ashrrev_i32_e32 v41, 31, v40
	v_lshlrev_b64 v[40:41], 7, v[40:41]
	v_lshl_add_u64 v[44:45], v[48:49], 0, v[40:41]
	global_load_dwordx4 v[40:43], v[44:45], off offset:16
	s_nop 0
	global_load_dwordx4 v[44:47], v[44:45], off
	s_nop 1
	ds_write_b32 v214, v16
	ds_write_b32 v215, v17
	ds_write_b32 v216, v18
	ds_write_b32 v217, v19
	ds_write_b32 v218, v20
	ds_write_b32 v219, v21
	ds_write_b32 v220, v22
	ds_write_b32 v221, v23
	ds_write_b32 v222, v24
	ds_write_b32 v223, v25
	ds_write_b32 v224, v26
	ds_write_b32 v225, v27
	ds_write_b32 v226, v28
	ds_write_b32 v227, v29
	ds_write_b32 v228, v30
	ds_write_b32 v229, v31
	s_waitcnt lgkmcnt(0)
	s_barrier
; #define LAS __attribute__((address_space(3)))
; __device__ __forceinline__ void gla_scan_phase2(LAS unsigned char* lds, const bf16_t* proj, const float* gbuf, const float* wgu  , const float* bg  ,
;                                                 bf16_t* ob0, bf16_t* ob1) {
;     ...
;                     float cs[16];
; #pragma unroll
;                     for (int ii = 0; ii < 16; ++ii) {
;                         const float z = *(const LAS float*)(lds + G2_Z + ((16 * seg + ii) * 128 + d) * 4);
;                         cs[ii] = fminf(z, 0.f) * (1.4426950408889634f / 16.f) - __builtin_amdgcn_logf(1.f + __builtin_amdgcn_exp2f(fabsf(z) * -1.4426950408889634f)) * (1.f / 16.f);
;                     }
;                     if (dir == 0) {
; #pragma unroll
;                         for (int ii = 1; ii < 16; ++ii) cs[ii] += cs[ii - 1];
;                         *(LAS float*)(lds + G2_SEG + (seg * 128 + d) * 4) = cs[15];
;                     } else {
; #pragma unroll
;     ...
;                         *(LAS float*)(lds + G2_SEG + (seg * 128 + d) * 4) = cs[0];
	ds_read2st64_b32 v[118:119], v230 offset1:2
	ds_read2st64_b32 v[120:121], v230 offset0:4 offset1:6
	ds_read2st64_b32 v[122:123], v230 offset0:8 offset1:10
	ds_read2st64_b32 v[124:125], v230 offset0:12 offset1:14
	ds_read2st64_b32 v[126:127], v230 offset0:16 offset1:18
	ds_read2st64_b32 v[128:129], v230 offset0:20 offset1:22
	ds_read2st64_b32 v[130:131], v230 offset0:24 offset1:26
	ds_read2st64_b32 v[132:133], v230 offset0:28 offset1:30
	s_andn2_b64 vcc, exec, s[68:69]
	s_mov_b64 s[6:7], -1
	s_waitcnt lgkmcnt(4)
	v_mul_f32_e64 v134, |v118|, s1
	v_mul_f32_e64 v135, |v119|, s1
	v_mul_f32_e64 v136, |v120|, s1
	v_mul_f32_e64 v137, |v121|, s1
	v_mul_f32_e64 v138, |v122|, s1
	v_mul_f32_e64 v139, |v123|, s1
	v_mul_f32_e64 v140, |v124|, s1
	v_mul_f32_e64 v141, |v125|, s1
	s_waitcnt lgkmcnt(0)
	v_mul_f32_e64 v142, |v126|, s1
	v_mul_f32_e64 v143, |v127|, s1
	v_mul_f32_e64 v144, |v128|, s1
	v_mul_f32_e64 v145, |v129|, s1
	v_mul_f32_e64 v146, |v130|, s1
	v_mul_f32_e64 v147, |v131|, s1
	v_mul_f32_e64 v148, |v132|, s1
	v_mul_f32_e64 v149, |v133|, s1
	v_exp_f32_e32 v134, v134
	v_exp_f32_e32 v135, v135
	v_exp_f32_e32 v136, v136
	v_exp_f32_e32 v137, v137
	v_exp_f32_e32 v138, v138
	v_exp_f32_e32 v139, v139
	v_exp_f32_e32 v140, v140
	v_exp_f32_e32 v141, v141
	v_exp_f32_e32 v142, v142
	v_exp_f32_e32 v143, v143
	v_exp_f32_e32 v144, v144
	v_exp_f32_e32 v145, v145
	v_exp_f32_e32 v146, v146
	v_exp_f32_e32 v147, v147
	v_exp_f32_e32 v148, v148
	v_exp_f32_e32 v149, v149
	v_min_f32_e32 v118, 0, v118
	v_min_f32_e32 v119, 0, v119
	v_min_f32_e32 v120, 0, v120
	v_min_f32_e32 v121, 0, v121
	v_min_f32_e32 v122, 0, v122
	v_min_f32_e32 v123, 0, v123
	v_min_f32_e32 v124, 0, v124
	v_min_f32_e32 v125, 0, v125
	v_min_f32_e32 v126, 0, v126
	v_min_f32_e32 v127, 0, v127
	v_min_f32_e32 v128, 0, v128
	v_min_f32_e32 v129, 0, v129
	v_min_f32_e32 v130, 0, v130
	v_min_f32_e32 v131, 0, v131
	v_min_f32_e32 v132, 0, v132
	v_min_f32_e32 v133, 0, v133
	v_add_f32_e32 v134, 1.0, v134
	v_add_f32_e32 v135, 1.0, v135
	v_add_f32_e32 v136, 1.0, v136
	v_add_f32_e32 v137, 1.0, v137
	v_add_f32_e32 v138, 1.0, v138
	v_add_f32_e32 v139, 1.0, v139
	v_add_f32_e32 v140, 1.0, v140
	v_add_f32_e32 v141, 1.0, v141
	v_add_f32_e32 v142, 1.0, v142
	v_add_f32_e32 v143, 1.0, v143
	v_add_f32_e32 v144, 1.0, v144
	v_add_f32_e32 v145, 1.0, v145
	v_add_f32_e32 v146, 1.0, v146
	v_add_f32_e32 v147, 1.0, v147
	v_add_f32_e32 v148, 1.0, v148
	v_add_f32_e32 v149, 1.0, v149
	v_log_f32_e32 v134, v134
	v_log_f32_e32 v135, v135
	v_log_f32_e32 v136, v136
	v_log_f32_e32 v137, v137
	v_log_f32_e32 v138, v138
	v_log_f32_e32 v139, v139
	v_log_f32_e32 v140, v140
	v_log_f32_e32 v141, v141
	v_log_f32_e32 v142, v142
	v_log_f32_e32 v143, v143
	v_log_f32_e32 v144, v144
	v_log_f32_e32 v145, v145
	v_log_f32_e32 v146, v146
	v_log_f32_e32 v147, v147
	v_log_f32_e32 v148, v148
	v_log_f32_e32 v149, v149
	v_mul_f32_e32 v134, 0x3d800000, v134
	v_mul_f32_e32 v135, 0x3d800000, v135
	v_mul_f32_e32 v136, 0x3d800000, v136
	v_mul_f32_e32 v137, 0x3d800000, v137
	v_mul_f32_e32 v138, 0x3d800000, v138
	v_mul_f32_e32 v139, 0x3d800000, v139
	v_mul_f32_e32 v140, 0x3d800000, v140
	v_mul_f32_e32 v141, 0x3d800000, v141
	v_mul_f32_e32 v142, 0x3d800000, v142
	v_mul_f32_e32 v143, 0x3d800000, v143
	v_mul_f32_e32 v144, 0x3d800000, v144
	v_mul_f32_e32 v145, 0x3d800000, v145
	v_mul_f32_e32 v146, 0x3d800000, v146
	v_mul_f32_e32 v147, 0x3d800000, v147
	v_mul_f32_e32 v148, 0x3d800000, v148
	v_mul_f32_e32 v149, 0x3d800000, v149
	v_fma_f32 v16, v118, s10, -v134
	v_fma_f32 v25, v119, s10, -v135
	v_fma_f32 v26, v120, s10, -v136
	v_fma_f32 v29, v121, s10, -v137
	v_fma_f32 v30, v122, s10, -v138
	v_fma_f32 v102, v123, s10, -v139
	v_fma_f32 v104, v124, s10, -v140
	v_fma_f32 v105, v125, s10, -v141
	v_fma_f32 v108, v126, s10, -v142
	v_fma_f32 v109, v127, s10, -v143
	v_fma_f32 v111, v128, s10, -v144
	v_fma_f32 v112, v129, s10, -v145
	v_fma_f32 v113, v130, s10, -v146
	v_fma_f32 v114, v131, s10, -v147
	v_fma_f32 v116, v132, s10, -v148
	v_fma_f32 v17, v133, s10, -v149
	s_cbranch_vccnz .LBB0_222
	v_add_f32_e32 v18, v116, v17
	v_add_f32_e32 v19, v114, v18
	v_add_f32_e32 v20, v113, v19
	v_add_f32_e32 v21, v112, v20
	v_add_f32_e32 v22, v111, v21
	v_add_f32_e32 v23, v109, v22
	v_add_f32_e32 v24, v108, v23
	v_add_f32_e32 v27, v105, v24
	v_add_f32_e32 v28, v104, v27
	v_add_f32_e32 v31, v102, v28
	v_add_f32_e32 v103, v30, v31
	v_add_f32_e32 v106, v29, v103
	v_add_f32_e32 v107, v26, v106
	v_add_f32_e32 v110, v25, v107
	v_add_f32_e32 v115, v16, v110
	s_mov_b64 s[6:7], 0

; #define LAS __attribute__((address_space(3)))
; __device__ __forceinline__ float bf2f(unsigned u16) { return __uint_as_float(u16 << 16); }
; #define G2_BAR() do { asm volatile("s_waitcnt lgkmcnt(0)" ::: "memory"); __builtin_amdgcn_s_barrier(); asm volatile("" ::: "memory"); } while (0)
; __device__ __forceinline__ void gla_scan_phase2(LAS unsigned char* lds, const bf16_t* proj, const float* gbuf, const float* wgu  , const float* bg  ,
;                                                 bf16_t* ob0, bf16_t* ob1) {
;     ...
;                         *(LAS float*)(lds + G2_SEG + (seg * 128 + d) * 4) = cs[0];
;                     }
;                     G2_BAR();
;                     {
;                         const float t0 = *(const LAS float*)(lds + G2_SEG + d * 4), t1 = *(const LAS float*)(lds + G2_SEG + (128 + d) * 4);
;                         const float prefix = dir == 0 ? (seg ? t0 : 0.f) : (seg ? 0.f : t1);
;                         const float ebl = __builtin_amdgcn_exp2f(t0 + t1);
;                         unsigned kd[8];
; #pragma unroll
;                         for (int ii = 0; ii < 16; ii += 2) {
;                             const float e0 = __builtin_amdgcn_exp2f(prefix + cs[ii]), e1 = __builtin_amdgcn_exp2f(prefix + cs[ii + 1]);
;                             const float q0 = bf2f(qv[ii]), q1 = bf2f(qv[ii + 1]);
;                             const float k0 = bf2f(kv[ii]) * __builtin_amdgcn_rcpf(e0), k1 = bf2f(kv[ii + 1]) * __builtin_amdgcn_rcpf(e1);
.LBB0_225:
	s_waitcnt vmcnt(18)
	ds_write_b32 v231, v115
	s_waitcnt lgkmcnt(0)
	s_barrier
	v_add_u32_e32 v25, s11, v202
	ds_read2st64_b32 v[104:105], v25 offset1:2
	ds_read_u16 v98, v173
	ds_read_u16 v100, v173 offset:256
	ds_read_u16 v94, v173 offset:512
	ds_read_u16 v96, v173 offset:768
	ds_read_u16 v90, v173 offset:1024
	ds_read_u16 v92, v173 offset:1280
	ds_read_u16 v82, v173 offset:1536
	ds_read_u16 v84, v173 offset:1792
	ds_read_u16 v99, v173 offset:8192
	ds_read_u16 v101, v173 offset:8448
	ds_read_u16 v95, v173 offset:8704
	ds_read_u16 v97, v173 offset:8960
	ds_read_u16 v91, v173 offset:9216
	ds_read_u16 v93, v173 offset:9472
	ds_read_u16 v83, v173 offset:9728
	ds_read_u16 v85, v173 offset:9984
	ds_read_u16 v86, v173 offset:2048
	ds_read_u16 v88, v173 offset:2304
	ds_read_u16 v78, v173 offset:2560
	ds_read_u16 v80, v173 offset:2816
	ds_read_u16 v74, v173 offset:3072
	ds_read_u16 v76, v173 offset:3328
	ds_read_u16 v70, v173 offset:3584
	ds_read_u16 v72, v173 offset:3840
	ds_read_u16 v87, v173 offset:10240
	ds_read_u16 v89, v173 offset:10496
	ds_read_u16 v79, v173 offset:10752
	ds_read_u16 v81, v173 offset:11008
	ds_read_u16 v75, v173 offset:11264
	ds_read_u16 v77, v173 offset:11520
	ds_read_u16 v71, v173 offset:11776
	ds_read_u16 v73, v173 offset:12032
	s_bitcmp1_b32 s20, 0
	s_cselect_b32 s0, 0xa800, 0
	s_waitcnt lgkmcnt(0)
	v_lshlrev_b32_e32 v111, 16, v100
	s_add_i32 s15, s0, 0
	s_waitcnt lgkmcnt(0)
; #define LAS __attribute__((address_space(3)))
; __device__ __forceinline__ unsigned pk2(float lo, float hi) { f32x2 v = {lo, hi}; bf16x2_t b = __builtin_convertvector(v, bf16x2_t); return __builtin_bit_cast(unsigned, b); }
; __device__ __forceinline__ void gla_scan_phase2(LAS unsigned char* lds, const bf16_t* proj, const float* gbuf, const float* wgu  , const float* bg  ,
;                                                 bf16_t* ob0, bf16_t* ob1) {
;     ...
;                         const float t0 = *(const LAS float*)(lds + G2_SEG + d * 4), t1 = *(const LAS float*)(lds + G2_SEG + (128 + d) * 4);
;                         const float prefix = dir == 0 ? (seg ? t0 : 0.f) : (seg ? 0.f : t1);
;                         const float ebl = __builtin_amdgcn_exp2f(t0 + t1);
;                         unsigned kd[8];
; #pragma unroll
;                         for (int ii = 0; ii < 16; ii += 2) {
;                             const float e0 = __builtin_amdgcn_exp2f(prefix + cs[ii]), e1 = __builtin_amdgcn_exp2f(prefix + cs[ii + 1]);
;                             const float q0 = bf2f(qv[ii]), q1 = bf2f(qv[ii + 1]);
;                             const float k0 = bf2f(kv[ii]) * __builtin_amdgcn_rcpf(e0), k1 = bf2f(kv[ii + 1]) * __builtin_amdgcn_rcpf(e1);
;                             const unsigned qd = pk2(q0 * e0, q1 * e1);
;                             const unsigned ki = pk2(k0, k1);
;                             kd[ii >> 1] = pk2(k0 * ebl, k1 * ebl);
;                             const int i0 = 16 * seg + ii;
;                             *(LAS unsigned short*)(set + G2_QD + i0 * 272 + d * 2) = (unsigned short)(qd & 0xffffu);
;                             *(LAS unsigned short*)(set + G2_QD + (i0 + 1) * 272 + d * 2) = (unsigned short)(qd >> 16);
;                             *(LAS unsigned short*)(lds + G2_KI + i0 * 272 + d * 2) = (unsigned short)(ki & 0xffffu);
;                             *(LAS unsigned short*)(lds + G2_KI + (i0 + 1) * 272 + d * 2) = (unsigned short)(ki >> 16);
;                         }
;                         *(LAS u32x4*)(set + G2_KDT + d * 80 + seg * 32) = (u32x4){kd[0], kd[1], kd[2], kd[3]};
;                         *(LAS u32x4*)(set + G2_KDT + d * 80 + seg * 32 + 16) = (u32x4){kd[4], kd[5], kd[6], kd[7]};
;                         if (seg == 0) *(LAS float*)(set + G2_EBL + d * 4) = ebl;
	v_cndmask_b32_e64 v25, v104, 0, s[38:39]
	v_cndmask_b32_e64 v26, 0, v105, s[38:39]
	v_cndmask_b32_e64 v102, v26, v25, s[48:49]
	v_add_f32_e32 v16, v16, v102
	v_exp_f32_e32 v108, v16
	v_add_f32_e32 v16, v110, v102
	v_exp_f32_e32 v109, v16
	v_add_f32_e32 v16, v104, v105
	v_rcp_f32_e32 v104, v108
	v_lshlrev_b32_e32 v110, 16, v98
	v_rcp_f32_e32 v105, v109
	v_pk_mul_f32 v[108:109], v[108:109], v[110:111]
	s_nop 0
	v_lshlrev_b32_e32 v101, 16, v101
	v_cvt_pk_bf16_f32 v25, v108, v109
	v_add3_u32 v108, s15, v201, v211
	v_lshlrev_b32_e32 v100, 16, v99
	ds_write_b16 v108, v25
	ds_write_b16_d16_hi v108, v25 offset:272
	v_add_f32_e32 v25, v107, v102
	v_pk_mul_f32 v[98:99], v[104:105], v[100:101]
	v_exp_f32_e32 v100, v25
	v_add_f32_e32 v25, v106, v102
	v_exp_f32_e32 v101, v25
	v_lshlrev_b32_e32 v107, 16, v96
	v_lshlrev_b32_e32 v106, 16, v94
	v_rcp_f32_e32 v104, v100
	v_rcp_f32_e32 v105, v101
	v_pk_mul_f32 v[100:101], v[100:101], v[106:107]
	v_cvt_pk_bf16_f32 v26, v98, v99
	v_cvt_pk_bf16_f32 v25, v100, v101
	ds_write_b16 v232, v26
	ds_write_b16_d16_hi v232, v26 offset:272
	ds_write_b16 v108, v25 offset:544
	ds_write_b16_d16_hi v108, v25 offset:816
	v_add_f32_e32 v25, v103, v102
	v_exp_f32_e32 v16, v16
	v_exp_f32_e32 v30, v25
	v_add_f32_e32 v25, v31, v102
	v_exp_f32_e32 v31, v25
	s_nop 0
	v_lshlrev_b32_e32 v97, 16, v97
	v_lshlrev_b32_e32 v96, 16, v95
	v_pk_mul_f32 v[94:95], v[104:105], v[96:97]
	v_pk_mul_f32 v[98:99], v[16:17], v[98:99] op_sel_hi:[0,1]
	v_cvt_pk_bf16_f32 v26, v94, v95
	v_pk_mul_f32 v[94:95], v[16:17], v[94:95] op_sel_hi:[0,1]
	v_lshlrev_b32_e32 v97, 16, v92
	v_lshlrev_b32_e32 v96, 16, v90
	v_cvt_pk_bf16_f32 v98, v98, v99
	v_cvt_pk_bf16_f32 v99, v94, v95
	v_rcp_f32_e32 v94, v30
	v_rcp_f32_e32 v95, v31
	v_pk_mul_f32 v[30:31], v[30:31], v[96:97]
	ds_write_b16 v232, v26 offset:544
	ds_write_b16_d16_hi v232, v26 offset:816
	v_cvt_pk_bf16_f32 v25, v30, v31
	ds_write_b16 v108, v25 offset:1088
	ds_write_b16_d16_hi v108, v25 offset:1360
	v_add_f32_e32 v25, v28, v102
	v_exp_f32_e32 v26, v25
	v_add_f32_e32 v25, v27, v102
	v_exp_f32_e32 v27, v25
	s_nop 0
	v_lshlrev_b32_e32 v31, 16, v93
	v_lshlrev_b32_e32 v30, 16, v91
	v_pk_mul_f32 v[30:31], v[94:95], v[30:31]
	v_rcp_f32_e32 v28, v26
	v_cvt_pk_bf16_f32 v29, v30, v31
	v_pk_mul_f32 v[30:31], v[16:17], v[30:31] op_sel_hi:[0,1]
	v_cvt_pk_bf16_f32 v100, v30, v31
	ds_write_b16 v232, v29 offset:1088
	ds_write_b16_d16_hi v232, v29 offset:1360
	v_rcp_f32_e32 v29, v27
	v_lshlrev_b32_e32 v31, 16, v84
	v_lshlrev_b32_e32 v30, 16, v82
	v_pk_mul_f32 v[26:27], v[26:27], v[30:31]
	v_add_f32_e32 v24, v24, v102
	v_cvt_pk_bf16_f32 v25, v26, v27
	v_add_f32_e32 v23, v23, v102
	s_nop 0
	v_lshlrev_b32_e32 v27, 16, v85
	v_lshlrev_b32_e32 v26, 16, v83
	ds_write_b16 v108, v25 offset:1632
	ds_write_b16_d16_hi v108, v25 offset:1904
	v_exp_f32_e32 v24, v24
	v_exp_f32_e32 v25, v23
	v_pk_mul_f32 v[26:27], v[28:29], v[26:27]
	s_nop 0
	v_lshlrev_b32_e32 v29, 16, v88
	v_cvt_pk_bf16_f32 v28, v26, v27
	v_pk_mul_f32 v[26:27], v[16:17], v[26:27] op_sel_hi:[0,1]
	ds_write_b16 v232, v28 offset:1632
	ds_write_b16_d16_hi v232, v28 offset:1904
	v_lshlrev_b32_e32 v28, 16, v86
	v_cvt_pk_bf16_f32 v101, v26, v27
	v_rcp_f32_e32 v26, v24
	v_rcp_f32_e32 v27, v25
	v_pk_mul_f32 v[24:25], v[24:25], v[28:29]
	v_add_f32_e32 v22, v22, v102
	v_cvt_pk_bf16_f32 v23, v24, v25
	v_add_f32_e32 v21, v21, v102
	ds_write_b16 v108, v23 offset:2176
	ds_write_b16_d16_hi v108, v23 offset:2448
	v_exp_f32_e32 v22, v22
	v_exp_f32_e32 v23, v21
	s_nop 0
	v_lshlrev_b32_e32 v25, 16, v89
	v_lshlrev_b32_e32 v24, 16, v87
	v_pk_mul_f32 v[24:25], v[26:27], v[24:25]
	v_lshlrev_b32_e32 v29, 16, v80
	v_cvt_pk_bf16_f32 v26, v24, v25
	v_lshlrev_b32_e32 v28, 16, v78
	ds_write_b16 v232, v26 offset:2176
	ds_write_b16_d16_hi v232, v26 offset:2448
	v_rcp_f32_e32 v26, v22
	v_rcp_f32_e32 v27, v23
	v_pk_mul_f32 v[22:23], v[22:23], v[28:29]
	v_add_f32_e32 v20, v20, v102
	v_cvt_pk_bf16_f32 v21, v22, v23
	v_add_f32_e32 v19, v19, v102
	ds_write_b16 v108, v21 offset:2720
	ds_write_b16_d16_hi v108, v21 offset:2992
	v_exp_f32_e32 v20, v20
	v_exp_f32_e32 v21, v19
	s_nop 0
	v_lshlrev_b32_e32 v23, 16, v81
	v_lshlrev_b32_e32 v22, 16, v79
	v_pk_mul_f32 v[22:23], v[26:27], v[22:23]
	v_pk_mul_f32 v[24:25], v[16:17], v[24:25] op_sel_hi:[0,1]
	v_cvt_pk_bf16_f32 v26, v22, v23
	v_pk_mul_f32 v[22:23], v[16:17], v[22:23] op_sel_hi:[0,1]
	v_cvt_pk_bf16_f32 v24, v24, v25
	v_cvt_pk_bf16_f32 v25, v22, v23
	v_rcp_f32_e32 v22, v20
	v_rcp_f32_e32 v23, v21
	ds_write_b16 v232, v26 offset:2720
	ds_write_b16_d16_hi v232, v26 offset:2992
	v_lshlrev_b32_e32 v27, 16, v76
	v_lshlrev_b32_e32 v26, 16, v74
	v_pk_mul_f32 v[20:21], v[20:21], v[26:27]
	v_add_f32_e32 v18, v18, v102
	v_cvt_pk_bf16_f32 v19, v20, v21
	s_nop 0
	v_lshlrev_b32_e32 v21, 16, v77
	v_lshlrev_b32_e32 v20, 16, v75
	v_pk_mul_f32 v[20:21], v[22:23], v[20:21]
	ds_write_b16 v108, v19 offset:3264
	ds_write_b16_d16_hi v108, v19 offset:3536
	v_cvt_pk_bf16_f32 v22, v20, v21
	v_pk_mul_f32 v[20:21], v[16:17], v[20:21] op_sel_hi:[0,1]
	v_add_f32_e32 v17, v17, v102
	v_exp_f32_e32 v18, v18
	v_exp_f32_e32 v19, v17
	v_cvt_pk_bf16_f32 v26, v20, v21
	ds_write_b16 v232, v22 offset:3264
	ds_write_b16_d16_hi v232, v22 offset:3536
	v_rcp_f32_e32 v20, v18
	v_rcp_f32_e32 v21, v19
	v_lshlrev_b32_e32 v23, 16, v72
	v_lshlrev_b32_e32 v22, 16, v70
	v_pk_mul_f32 v[18:19], v[18:19], v[22:23]
	s_nop 0
	v_cvt_pk_bf16_f32 v17, v18, v19
	s_nop 0
	v_lshlrev_b32_e32 v19, 16, v73
	v_lshlrev_b32_e32 v18, 16, v71
	v_pk_mul_f32 v[18:19], v[20:21], v[18:19]
	s_nop 0
	v_cvt_pk_bf16_f32 v20, v18, v19
	v_pk_mul_f32 v[18:19], v[16:17], v[18:19] op_sel_hi:[0,1]
	ds_write_b16 v108, v17 offset:3808
	ds_write_b16_d16_hi v108, v17 offset:4080
	ds_write_b16 v232, v20 offset:3808
	ds_write_b16_d16_hi v232, v20 offset:4080
	v_add3_u32 v17, s15, v203, v204
	v_cvt_pk_bf16_f32 v27, v18, v19
	ds_write_b128 v17, v[98:101] offset:8704
	ds_write_b128 v17, v[24:27] offset:8720
	s_and_saveexec_b64 s[6:7], s[38:39]
	s_cbranch_execz .LBB0_219
	v_add_u32_e32 v17, s15, v202
	ds_write_b32 v17, v16 offset:41984
	s_branch .LBB0_219
